# attention units: end-of-unit hand-off write and workgroup barrier removed (hand-off happens at the end of the first pair)
# speedup vs baseline: 1.0088x; 1.0088x over previous
.LBB0_209:
	s_or_b64 exec, exec, s[4:5]
	s_lshl_b32 s4, s21, 2
	s_add_i32 s4, s4, 0
	s_add_i32 s4, s4, 0x15500
	v_mov_b32_e32 v0, s4
	s_waitcnt lgkmcnt(0)
	ds_read_b32 v0, v0
	s_waitcnt lgkmcnt(0)
	v_cmp_lt_i32_e32 vcc, s45, v0
	v_readfirstlane_b32 s38, v0
	s_cbranch_vccnz .LBB0_261

.LBB0_259:
	v_div_scale_f32 v35, s[4:5], v34, v34, 1.0
	v_rcp_f32_e32 v36, v35
	v_div_scale_f32 v37, vcc, 1.0, v34, 1.0
	v_mov_b32_e32 v161, v193
	v_fma_f32 v38, -v35, v36, 1.0
	v_fmac_f32_e32 v36, v38, v36
	v_mul_f32_e32 v38, v37, v36
	v_fma_f32 v39, -v35, v38, v37
	v_fmac_f32_e32 v38, v39, v36
	v_fma_f32 v35, -v35, v38, v37
	v_div_fmas_f32 v35, v35, v36, v38
	v_div_fixup_f32 v34, v35, v34, 1.0
	v_pk_mul_f32 v[16:17], v[16:17], v[34:35] op_sel_hi:[1,0]
	v_pk_mul_f32 v[18:19], v[18:19], v[34:35] op_sel_hi:[1,0]
	v_pk_mul_f32 v[0:1], v[34:35], v[0:1] op_sel_hi:[0,1]
	v_pk_mul_f32 v[2:3], v[34:35], v[2:3] op_sel_hi:[0,1]
	v_lshl_add_u64 v[32:33], v[160:161], 1, v[32:33]
	v_cvt_pk_bf16_f32 v16, v16, v17
	v_cvt_pk_bf16_f32 v17, v18, v19
	v_cvt_pk_bf16_f32 v0, v0, v1
	v_cvt_pk_bf16_f32 v1, v2, v3
	global_store_dwordx2 v[32:33], v[16:17], off
	global_store_dwordx2 v[32:33], v[0:1], off offset:64
	v_pk_mul_f32 v[0:1], v[20:21], v[34:35] op_sel_hi:[1,0]
	v_pk_mul_f32 v[2:3], v[22:23], v[34:35] op_sel_hi:[1,0]
	v_cvt_pk_bf16_f32 v0, v0, v1
	v_cvt_pk_bf16_f32 v1, v2, v3
	v_pk_mul_f32 v[2:3], v[34:35], v[4:5] op_sel_hi:[0,1]
	v_pk_mul_f32 v[4:5], v[34:35], v[6:7] op_sel_hi:[0,1]
	v_cvt_pk_bf16_f32 v2, v2, v3
	v_cvt_pk_bf16_f32 v3, v4, v5
	global_store_dwordx2 v[32:33], v[0:1], off offset:16
	global_store_dwordx2 v[32:33], v[2:3], off offset:80
	v_pk_mul_f32 v[0:1], v[24:25], v[34:35] op_sel_hi:[1,0]
	v_pk_mul_f32 v[2:3], v[26:27], v[34:35] op_sel_hi:[1,0]
	v_cvt_pk_bf16_f32 v0, v0, v1
	v_cvt_pk_bf16_f32 v1, v2, v3
	v_pk_mul_f32 v[2:3], v[34:35], v[8:9] op_sel_hi:[0,1]
	v_pk_mul_f32 v[4:5], v[34:35], v[10:11] op_sel_hi:[0,1]
	v_cvt_pk_bf16_f32 v2, v2, v3
	v_cvt_pk_bf16_f32 v3, v4, v5
	global_store_dwordx2 v[32:33], v[0:1], off offset:32
	global_store_dwordx2 v[32:33], v[2:3], off offset:96
	v_pk_mul_f32 v[0:1], v[28:29], v[34:35] op_sel_hi:[1,0]
	v_pk_mul_f32 v[2:3], v[30:31], v[34:35] op_sel_hi:[1,0]
	v_cvt_pk_bf16_f32 v0, v0, v1
	v_cvt_pk_bf16_f32 v1, v2, v3
	v_pk_mul_f32 v[2:3], v[34:35], v[12:13] op_sel_hi:[0,1]
	v_pk_mul_f32 v[4:5], v[34:35], v[14:15] op_sel_hi:[0,1]
	s_xor_b32 s21, s21, 1
	v_cvt_pk_bf16_f32 v2, v2, v3
	v_cvt_pk_bf16_f32 v3, v4, v5
	global_store_dwordx2 v[32:33], v[0:1], off offset:48
	global_store_dwordx2 v[32:33], v[2:3], off offset:112
	s_and_saveexec_b64 s[4:5], s[42:43]
	s_cbranch_execz .LBB0_209
	s_lshl_b32 s6, s21, 2
	s_add_i32 s6, s6, 0
	s_add_i32 s6, s6, 0x15500
	v_mov_b32_e32 v0, s6
	s_branch .LBB0_209

.LBB0_271:
	s_or_b64 exec, exec, s[4:5]
	s_lshl_b32 s4, s44, 2
	s_add_i32 s4, s4, 0
	s_add_i32 s4, s4, 0x15500
	v_mov_b32_e32 v0, s4
	s_waitcnt lgkmcnt(0)
	ds_read_b32 v0, v0
	s_waitcnt lgkmcnt(0)
	v_cmp_lt_i32_e32 vcc, s45, v0
	v_readfirstlane_b32 s37, v0
	s_cbranch_vccnz .LBB0_312

.LBB0_310:
	v_div_scale_f32 v35, s[4:5], v34, v34, 1.0
	v_rcp_f32_e32 v36, v35
	v_div_scale_f32 v37, vcc, 1.0, v34, 1.0
	v_mov_b32_e32 v137, v193
	v_fma_f32 v38, -v35, v36, 1.0
	v_fmac_f32_e32 v36, v38, v36
	v_mul_f32_e32 v38, v37, v36
	v_fma_f32 v39, -v35, v38, v37
	v_fmac_f32_e32 v38, v39, v36
	v_fma_f32 v35, -v35, v38, v37
	v_div_fmas_f32 v35, v35, v36, v38
	v_div_fixup_f32 v34, v35, v34, 1.0
	v_pk_mul_f32 v[16:17], v[16:17], v[34:35] op_sel_hi:[1,0]
	v_pk_mul_f32 v[18:19], v[18:19], v[34:35] op_sel_hi:[1,0]
	v_pk_mul_f32 v[0:1], v[34:35], v[0:1] op_sel_hi:[0,1]
	v_pk_mul_f32 v[2:3], v[34:35], v[2:3] op_sel_hi:[0,1]
	v_lshl_add_u64 v[32:33], v[136:137], 1, v[32:33]
	v_cvt_pk_bf16_f32 v16, v16, v17
	v_cvt_pk_bf16_f32 v17, v18, v19
	v_cvt_pk_bf16_f32 v0, v0, v1
	v_cvt_pk_bf16_f32 v1, v2, v3
	global_store_dwordx2 v[32:33], v[16:17], off
	global_store_dwordx2 v[32:33], v[0:1], off offset:64
	v_pk_mul_f32 v[0:1], v[20:21], v[34:35] op_sel_hi:[1,0]
	v_pk_mul_f32 v[2:3], v[22:23], v[34:35] op_sel_hi:[1,0]
	v_cvt_pk_bf16_f32 v0, v0, v1
	v_cvt_pk_bf16_f32 v1, v2, v3
	v_pk_mul_f32 v[2:3], v[34:35], v[4:5] op_sel_hi:[0,1]
	v_pk_mul_f32 v[4:5], v[34:35], v[6:7] op_sel_hi:[0,1]
	v_cvt_pk_bf16_f32 v2, v2, v3
	v_cvt_pk_bf16_f32 v3, v4, v5
	global_store_dwordx2 v[32:33], v[0:1], off offset:16
	global_store_dwordx2 v[32:33], v[2:3], off offset:80
	v_pk_mul_f32 v[0:1], v[24:25], v[34:35] op_sel_hi:[1,0]
	v_pk_mul_f32 v[2:3], v[26:27], v[34:35] op_sel_hi:[1,0]
	v_cvt_pk_bf16_f32 v0, v0, v1
	v_cvt_pk_bf16_f32 v1, v2, v3
	v_pk_mul_f32 v[2:3], v[34:35], v[8:9] op_sel_hi:[0,1]
	v_pk_mul_f32 v[4:5], v[34:35], v[10:11] op_sel_hi:[0,1]
	v_cvt_pk_bf16_f32 v2, v2, v3
	v_cvt_pk_bf16_f32 v3, v4, v5
	global_store_dwordx2 v[32:33], v[0:1], off offset:32
	global_store_dwordx2 v[32:33], v[2:3], off offset:96
	v_pk_mul_f32 v[0:1], v[28:29], v[34:35] op_sel_hi:[1,0]
	v_pk_mul_f32 v[2:3], v[30:31], v[34:35] op_sel_hi:[1,0]
	v_cvt_pk_bf16_f32 v0, v0, v1
	v_cvt_pk_bf16_f32 v1, v2, v3
	v_pk_mul_f32 v[2:3], v[34:35], v[12:13] op_sel_hi:[0,1]
	v_pk_mul_f32 v[4:5], v[34:35], v[14:15] op_sel_hi:[0,1]
	s_xor_b32 s44, s44, 1
	v_cvt_pk_bf16_f32 v2, v2, v3
	v_cvt_pk_bf16_f32 v3, v4, v5
	global_store_dwordx2 v[32:33], v[0:1], off offset:48
	global_store_dwordx2 v[32:33], v[2:3], off offset:112
	s_and_saveexec_b64 s[4:5], s[40:41]
	s_cbranch_execz .LBB0_271
	s_lshl_b32 s8, s44, 2
	s_add_i32 s8, s8, 0
	s_add_i32 s8, s8, 0x15500
	v_mov_b32_e32 v0, s8
	s_branch .LBB0_271
